# grid barrier: first arriver of each XCD issues an early buffer_wbl2 so the leader's final writeback is shorter
# baseline (speedup 1.0000x reference)
; __device__ __forceinline__ unsigned xb_ld(unsigned* p)              { return __hip_atomic_load(p, __ATOMIC_RELAXED, __HIP_MEMORY_SCOPE_AGENT); }
; __device__ __forceinline__ unsigned xb_add(unsigned* p, unsigned v) { return __hip_atomic_fetch_add(p, v, __ATOMIC_RELAXED, __HIP_MEMORY_SCOPE_AGENT); }
; #define XB_SPIN(cond, bar) do { unsigned _sp = 0; while (cond) { __builtin_amdgcn_s_sleep(1); \
;     if ((++_sp & 255u) == 0u) { if (xb_ld(&(bar)[XB_TMO])) break; if (_sp > XB_SPIN_CAP) { atomicAdd(&(bar)[XB_TMO], 1u); break; } } } } while (0)
; __device__ __forceinline__ void xcd_barrier(const XcdBarrier& b) {
;     ...
;         const unsigned old = xb_add(&bar[XB_XSUB(b.x)], 1u);
;         const unsigned gen = old / nloc;
;         if (old + 1u == (gen + 1u) * nloc) {
;             __builtin_amdgcn_fence(__ATOMIC_RELEASE, "agent");
;             asm volatile("s_waitcnt vmcnt(0)" ::: "memory");
;             const unsigned og = xb_add(&bar[XB_TOP], 1u);
;             const unsigned tg = og / nx;
;             if (og + 1u == (tg + 1u) * nx) xb_add(&bar[XB_TOPGEN], 1u);
;             else XB_SPIN(xb_ld(&bar[XB_TOPGEN]) == tg, bar);
.LBB0_278:
	s_lshl_b32 s0, s38, 8
	s_add_u32 s27, s40, s0
	s_addc_u32 s26, s41, 0
	v_mov_b32_e32 v1, s27
	v_add_co_u32_e32 v4, vcc, 0x1000, v1
	v_mov_b32_e32 v1, s26
	s_nop 0
	v_addc_co_u32_e32 v5, vcc, 0, v1, vcc
	flat_atomic_add v3, v[4:5], v225 offset:1024 sc0
	v_cvt_f32_u32_e32 v1, v2
	v_sub_u32_e32 v4, 0, v2
	v_rcp_iflag_f32_e32 v1, v1
	s_nop 0
	v_mul_f32_e32 v1, 0x4f7ffffe, v1
	v_cvt_u32_f32_e32 v1, v1
	v_mul_lo_u32 v4, v4, v1
	v_mul_hi_u32 v4, v1, v4
	v_add_u32_e32 v1, v1, v4
	s_waitcnt vmcnt(0) lgkmcnt(0)
	v_mul_hi_u32 v1, v3, v1
	v_mul_lo_u32 v4, v1, v2
	v_sub_u32_e32 v4, v3, v4
	v_cmp_ge_u32_e32 vcc, v4, v2
	v_add_u32_e32 v5, 1, v1
	s_nop 0
	v_cndmask_b32_e32 v1, v1, v5, vcc
	v_sub_u32_e32 v5, v4, v2
	v_cndmask_b32_e32 v4, v4, v5, vcc
	v_cmp_eq_u32_e32 vcc, 0, v4
	s_nop 1
	s_and_saveexec_b64 s[0:1], vcc
	s_cbranch_execz .Learlywb_0
	buffer_wbl2 sc1
.Learlywb_0:
	s_or_b64 exec, exec, s[0:1]
	v_cmp_ge_u32_e32 vcc, v4, v2
	v_add_u32_e32 v4, 1, v1
	s_nop 0
	v_cndmask_b32_e32 v1, v1, v4, vcc
	v_add_u32_e32 v4, 1, v3
	v_mad_u64_u32 v[2:3], s[0:1], v2, v1, v[2:3]
	v_cmp_ne_u32_e32 vcc, v4, v2
	s_and_saveexec_b64 s[0:1], vcc
	s_xor_b64 s[0:1], exec, s[0:1]
	s_cbranch_execz .LBB0_291
	v_mov_b32_e32 v0, s27
	v_add_co_u32_e32 v2, vcc, 0x2000, v0
	v_mov_b32_e32 v0, s26
	s_nop 0
	v_addc_co_u32_e32 v3, vcc, 0, v0, vcc
	flat_load_dword v0, v[2:3] offset:1024 sc1
	s_add_u32 s6, s27, 0x2400
	s_addc_u32 s7, s26, 0
	s_waitcnt vmcnt(0) lgkmcnt(0)
	v_cmp_eq_u32_e32 vcc, v0, v1
	s_and_saveexec_b64 s[4:5], vcc
	s_cbranch_execz .LBB0_290
	s_mov_b32 s28, 1
	s_mov_b64 s[10:11], 0
	s_branch .LBB0_282

; __device__ __forceinline__ unsigned xb_ld(unsigned* p)              { return __hip_atomic_load(p, __ATOMIC_RELAXED, __HIP_MEMORY_SCOPE_AGENT); }
; __device__ __forceinline__ unsigned xb_add(unsigned* p, unsigned v) { return __hip_atomic_fetch_add(p, v, __ATOMIC_RELAXED, __HIP_MEMORY_SCOPE_AGENT); }
; #define XB_SPIN(cond, bar) do { unsigned _sp = 0; while (cond) { __builtin_amdgcn_s_sleep(1); \
;     if ((++_sp & 255u) == 0u) { if (xb_ld(&(bar)[XB_TMO])) break; if (_sp > XB_SPIN_CAP) { atomicAdd(&(bar)[XB_TMO], 1u); break; } } } } while (0)
; __device__ __forceinline__ void xcd_barrier(const XcdBarrier& b) {
;     ...
;         const unsigned old = xb_add(&bar[XB_XSUB(b.x)], 1u);
;         const unsigned gen = old / nloc;
;         if (old + 1u == (gen + 1u) * nloc) {
;             __builtin_amdgcn_fence(__ATOMIC_RELEASE, "agent");
;             asm volatile("s_waitcnt vmcnt(0)" ::: "memory");
;             const unsigned og = xb_add(&bar[XB_TOP], 1u);
;             const unsigned tg = og / nx;
;             if (og + 1u == (tg + 1u) * nx) xb_add(&bar[XB_TOPGEN], 1u);
;             else XB_SPIN(xb_ld(&bar[XB_TOPGEN]) == tg, bar);
.LBB0_868:
	s_lshl_b32 s0, s36, 8
	s_add_u32 s25, s40, s0
	s_addc_u32 s24, s41, 0
	v_mov_b32_e32 v1, s25
	v_add_co_u32_e32 v4, vcc, 0x1000, v1
	v_mov_b32_e32 v1, s24
	s_nop 0
	v_addc_co_u32_e32 v5, vcc, 0, v1, vcc
	flat_atomic_add v3, v[4:5], v225 offset:1024 sc0
	v_cvt_f32_u32_e32 v1, v2
	v_sub_u32_e32 v4, 0, v2
	v_rcp_iflag_f32_e32 v1, v1
	s_nop 0
	v_mul_f32_e32 v1, 0x4f7ffffe, v1
	v_cvt_u32_f32_e32 v1, v1
	v_mul_lo_u32 v4, v4, v1
	v_mul_hi_u32 v4, v1, v4
	v_add_u32_e32 v1, v1, v4
	s_waitcnt vmcnt(0) lgkmcnt(0)
	v_mul_hi_u32 v1, v3, v1
	v_mul_lo_u32 v4, v1, v2
	v_sub_u32_e32 v4, v3, v4
	v_cmp_ge_u32_e32 vcc, v4, v2
	v_add_u32_e32 v5, 1, v1
	s_nop 0
	v_cndmask_b32_e32 v1, v1, v5, vcc
	v_sub_u32_e32 v5, v4, v2
	v_cndmask_b32_e32 v4, v4, v5, vcc
	v_cmp_eq_u32_e32 vcc, 0, v4
	s_nop 1
	s_and_saveexec_b64 s[0:1], vcc
	s_cbranch_execz .Learlywb_1
	buffer_wbl2 sc1
.Learlywb_1:
	s_or_b64 exec, exec, s[0:1]
	v_cmp_ge_u32_e32 vcc, v4, v2
	v_add_u32_e32 v4, 1, v1
	s_nop 0
	v_cndmask_b32_e32 v1, v1, v4, vcc
	v_add_u32_e32 v4, 1, v3
	v_mad_u64_u32 v[2:3], s[0:1], v2, v1, v[2:3]
	v_cmp_ne_u32_e32 vcc, v4, v2
	s_and_saveexec_b64 s[0:1], vcc
	s_xor_b64 s[0:1], exec, s[0:1]
	s_cbranch_execz .LBB0_881
	v_mov_b32_e32 v0, s25
	v_add_co_u32_e32 v2, vcc, 0x2000, v0
	v_mov_b32_e32 v0, s24
	s_nop 0
	v_addc_co_u32_e32 v3, vcc, 0, v0, vcc
	flat_load_dword v0, v[2:3] offset:1024 sc1
	s_add_u32 s6, s25, 0x2400
	s_addc_u32 s7, s24, 0
	s_waitcnt vmcnt(0) lgkmcnt(0)
	v_cmp_eq_u32_e32 vcc, v0, v1
	s_and_saveexec_b64 s[4:5], vcc
	s_cbranch_execz .LBB0_880
	s_mov_b32 s26, 1
	s_mov_b64 s[8:9], 0
	s_branch .LBB0_872

; __device__ __forceinline__ unsigned xb_ld(unsigned* p)              { return __hip_atomic_load(p, __ATOMIC_RELAXED, __HIP_MEMORY_SCOPE_AGENT); }
; __device__ __forceinline__ unsigned xb_add(unsigned* p, unsigned v) { return __hip_atomic_fetch_add(p, v, __ATOMIC_RELAXED, __HIP_MEMORY_SCOPE_AGENT); }
; #define XB_SPIN(cond, bar) do { unsigned _sp = 0; while (cond) { __builtin_amdgcn_s_sleep(1); \
;     if ((++_sp & 255u) == 0u) { if (xb_ld(&(bar)[XB_TMO])) break; if (_sp > XB_SPIN_CAP) { atomicAdd(&(bar)[XB_TMO], 1u); break; } } } } while (0)
; __device__ __forceinline__ void xcd_barrier(const XcdBarrier& b) {
;     ...
;         const unsigned old = xb_add(&bar[XB_XSUB(b.x)], 1u);
;         const unsigned gen = old / nloc;
;         if (old + 1u == (gen + 1u) * nloc) {
;             __builtin_amdgcn_fence(__ATOMIC_RELEASE, "agent");
;             asm volatile("s_waitcnt vmcnt(0)" ::: "memory");
;             const unsigned og = xb_add(&bar[XB_TOP], 1u);
;             const unsigned tg = og / nx;
;             if (og + 1u == (tg + 1u) * nx) xb_add(&bar[XB_TOPGEN], 1u);
;             else XB_SPIN(xb_ld(&bar[XB_TOPGEN]) == tg, bar);
.LBB0_1043:
	s_lshl_b32 s0, s16, 8
	s_add_u32 s17, s40, s0
	s_addc_u32 s16, s41, 0
	v_mov_b32_e32 v1, s17
	v_add_co_u32_e32 v4, vcc, 0x1000, v1
	v_mov_b32_e32 v1, s16
	s_nop 0
	v_addc_co_u32_e32 v5, vcc, 0, v1, vcc
	flat_atomic_add v3, v[4:5], v225 offset:1024 sc0
	v_cvt_f32_u32_e32 v1, v2
	v_sub_u32_e32 v4, 0, v2
	v_rcp_iflag_f32_e32 v1, v1
	s_nop 0
	v_mul_f32_e32 v1, 0x4f7ffffe, v1
	v_cvt_u32_f32_e32 v1, v1
	v_mul_lo_u32 v4, v4, v1
	v_mul_hi_u32 v4, v1, v4
	v_add_u32_e32 v1, v1, v4
	s_waitcnt vmcnt(0) lgkmcnt(0)
	v_mul_hi_u32 v1, v3, v1
	v_mul_lo_u32 v4, v1, v2
	v_sub_u32_e32 v4, v3, v4
	v_cmp_ge_u32_e32 vcc, v4, v2
	v_add_u32_e32 v5, 1, v1
	s_nop 0
	v_cndmask_b32_e32 v1, v1, v5, vcc
	v_sub_u32_e32 v5, v4, v2
	v_cndmask_b32_e32 v4, v4, v5, vcc
	v_cmp_eq_u32_e32 vcc, 0, v4
	s_nop 1
	s_and_saveexec_b64 s[0:1], vcc
	s_cbranch_execz .Learlywb_2
	buffer_wbl2 sc1
.Learlywb_2:
	s_or_b64 exec, exec, s[0:1]
	v_cmp_ge_u32_e32 vcc, v4, v2
	v_add_u32_e32 v4, 1, v1
	s_nop 0
	v_cndmask_b32_e32 v1, v1, v4, vcc
	v_add_u32_e32 v4, 1, v3
	v_mad_u64_u32 v[2:3], s[0:1], v2, v1, v[2:3]
	v_cmp_ne_u32_e32 vcc, v4, v2
	s_and_saveexec_b64 s[0:1], vcc
	s_xor_b64 s[0:1], exec, s[0:1]
	s_cbranch_execz .LBB0_1056
	v_mov_b32_e32 v0, s17
	v_add_co_u32_e32 v2, vcc, 0x2000, v0
	v_mov_b32_e32 v0, s16
	s_nop 0
	v_addc_co_u32_e32 v3, vcc, 0, v0, vcc
	flat_load_dword v0, v[2:3] offset:1024 sc1
	s_add_u32 s6, s17, 0x2400
	s_addc_u32 s7, s16, 0
	s_waitcnt vmcnt(0) lgkmcnt(0)
	v_cmp_eq_u32_e32 vcc, v0, v1
	s_and_saveexec_b64 s[4:5], vcc
	s_cbranch_execz .LBB0_1055
	s_mov_b32 s26, 1
	s_mov_b64 s[8:9], 0
	s_branch .LBB0_1047

; __device__ __forceinline__ unsigned xb_ld(unsigned* p)              { return __hip_atomic_load(p, __ATOMIC_RELAXED, __HIP_MEMORY_SCOPE_AGENT); }
; __device__ __forceinline__ unsigned xb_add(unsigned* p, unsigned v) { return __hip_atomic_fetch_add(p, v, __ATOMIC_RELAXED, __HIP_MEMORY_SCOPE_AGENT); }
; #define XB_SPIN(cond, bar) do { unsigned _sp = 0; while (cond) { __builtin_amdgcn_s_sleep(1); \
;     if ((++_sp & 255u) == 0u) { if (xb_ld(&(bar)[XB_TMO])) break; if (_sp > XB_SPIN_CAP) { atomicAdd(&(bar)[XB_TMO], 1u); break; } } } } while (0)
; __device__ __forceinline__ void xcd_barrier(const XcdBarrier& b) {
;     ...
;         const unsigned old = xb_add(&bar[XB_XSUB(b.x)], 1u);
;         const unsigned gen = old / nloc;
;         if (old + 1u == (gen + 1u) * nloc) {
;             __builtin_amdgcn_fence(__ATOMIC_RELEASE, "agent");
;             asm volatile("s_waitcnt vmcnt(0)" ::: "memory");
;             const unsigned og = xb_add(&bar[XB_TOP], 1u);
;             const unsigned tg = og / nx;
;             if (og + 1u == (tg + 1u) * nx) xb_add(&bar[XB_TOPGEN], 1u);
;             else XB_SPIN(xb_ld(&bar[XB_TOPGEN]) == tg, bar);
.Learlywb_3:
	s_or_b64 exec, exec, s[0:1]
	v_cmp_ge_u32_e32 vcc, v4, v2
	v_add_u32_e32 v4, 1, v1
	s_nop 0
	v_cndmask_b32_e32 v1, v1, v4, vcc
	v_add_u32_e32 v4, 1, v3
	v_mad_u64_u32 v[2:3], s[0:1], v2, v1, v[2:3]
	v_cmp_ne_u32_e32 vcc, v4, v2
	s_and_saveexec_b64 s[0:1], vcc
	s_xor_b64 s[0:1], exec, s[0:1]
	s_cbranch_execz .LBB0_1145
	v_mov_b32_e32 v0, s17
	v_add_co_u32_e32 v2, vcc, 0x2000, v0
	v_mov_b32_e32 v0, s16
	s_nop 0
	v_addc_co_u32_e32 v3, vcc, 0, v0, vcc
	flat_load_dword v0, v[2:3] offset:1024 sc1
	s_add_u32 s8, s17, 0x2400
	s_addc_u32 s9, s16, 0
	s_waitcnt vmcnt(0) lgkmcnt(0)
	v_cmp_eq_u32_e32 vcc, v0, v1
	s_and_saveexec_b64 s[6:7], vcc
	s_cbranch_execz .LBB0_1144
	s_mov_b32 s28, 1
	s_mov_b64 s[10:11], 0
	s_branch .LBB0_1136

; __device__ __forceinline__ unsigned xb_ld(unsigned* p)              { return __hip_atomic_load(p, __ATOMIC_RELAXED, __HIP_MEMORY_SCOPE_AGENT); }
; __device__ __forceinline__ unsigned xb_add(unsigned* p, unsigned v) { return __hip_atomic_fetch_add(p, v, __ATOMIC_RELAXED, __HIP_MEMORY_SCOPE_AGENT); }
; #define XB_SPIN(cond, bar) do { unsigned _sp = 0; while (cond) { __builtin_amdgcn_s_sleep(1); \
;     if ((++_sp & 255u) == 0u) { if (xb_ld(&(bar)[XB_TMO])) break; if (_sp > XB_SPIN_CAP) { atomicAdd(&(bar)[XB_TMO], 1u); break; } } } } while (0)
; __device__ __forceinline__ void xcd_barrier(const XcdBarrier& b) {
;     ...
;         const unsigned old = xb_add(&bar[XB_XSUB(b.x)], 1u);
;         const unsigned gen = old / nloc;
;         if (old + 1u == (gen + 1u) * nloc) {
;             __builtin_amdgcn_fence(__ATOMIC_RELEASE, "agent");
;             asm volatile("s_waitcnt vmcnt(0)" ::: "memory");
;             const unsigned og = xb_add(&bar[XB_TOP], 1u);
;             const unsigned tg = og / nx;
;             if (og + 1u == (tg + 1u) * nx) xb_add(&bar[XB_TOPGEN], 1u);
;             else XB_SPIN(xb_ld(&bar[XB_TOPGEN]) == tg, bar);
.LBB0_1300:
	s_lshl_b32 s0, s38, 8
	s_add_u32 s25, s36, s0
	s_addc_u32 s24, s37, 0
	v_mov_b32_e32 v1, s25
	v_add_co_u32_e32 v4, vcc, 0x1000, v1
	v_mov_b32_e32 v1, s24
	s_nop 0
	v_addc_co_u32_e32 v5, vcc, 0, v1, vcc
	flat_atomic_add v3, v[4:5], v225 offset:1024 sc0
	v_cvt_f32_u32_e32 v1, v2
	v_sub_u32_e32 v4, 0, v2
	v_rcp_iflag_f32_e32 v1, v1
	s_nop 0
	v_mul_f32_e32 v1, 0x4f7ffffe, v1
	v_cvt_u32_f32_e32 v1, v1
	v_mul_lo_u32 v4, v4, v1
	v_mul_hi_u32 v4, v1, v4
	v_add_u32_e32 v1, v1, v4
	s_waitcnt vmcnt(0) lgkmcnt(0)
	v_mul_hi_u32 v1, v3, v1
	v_mul_lo_u32 v4, v1, v2
	v_sub_u32_e32 v4, v3, v4
	v_cmp_ge_u32_e32 vcc, v4, v2
	v_add_u32_e32 v5, 1, v1
	s_nop 0
	v_cndmask_b32_e32 v1, v1, v5, vcc
	v_sub_u32_e32 v5, v4, v2
	v_cndmask_b32_e32 v4, v4, v5, vcc
	v_cmp_eq_u32_e32 vcc, 0, v4
	s_nop 1
	s_and_saveexec_b64 s[0:1], vcc
	s_cbranch_execz .Learlywb_4
	buffer_wbl2 sc1
